# attnA main loop: every 8-byte instruction on an 8-byte boundary (3 VALU re-encoded as e64, 11 s_nop after waits)
# baseline (speedup 1.0000x reference)
; #define LAS __attribute__((address_space(3)))
; __device__ __forceinline__ float fexp2(float x) { return __builtin_amdgcn_exp2f(x); }
; #define MFMA32(a, b, c) __builtin_amdgcn_mfma_f32_32x32x16_bf16((a), (b), (c), 0, 0, 0)
; __device__ __forceinline__ bf16x8 v_build(const VRaw& r, int ks) { return (bf16x8){r.lo[ks][0], r.lo[ks][1], r.lo[ks][2], r.lo[ks][3], r.hv[ks][0], r.hv[ks][1], r.hv[ks][2], r.hv[ks][3]}; }
; #define A_MAX() \
;         float mx = fmaxf(s[0][0], s[1][0]); \
;         _Pragma("unroll") for (int r = 1; r < 16; ++r) mx = fmaxf(fmaxf(mx, s[0][r]), s[1][r]); \
;         mx = fmaxf(mx, __shfl_xor(mx, 32));
; __device__ __forceinline__ void attnA_unit(const P2Ctx& C, int b, int h, int qb) {
;     ...
;     for (int kt = 1; kt < NT; ++kt) {
;         if (kt + 2 < NT && !(pf & 16)) A_DMA(kt + 2);
;         if (kt < ntw) {
;             A_QK(kt)
;             if (!(pf & 4)) {
;             const LAS unsigned char* vimg = lds + ((kt - 1) & 3) * 32768 + 16384;
;             VRaw va;
;             v_issue<4>(vimg, 0, lane, va);
;             A_MAX()
;             float fres = 1.0f; bool resc = false;
;             if (__any(mx > ATHR)) {
;                 const float dl = fmaxf(mx, 0.f);
;                 mhat += dl;
;                 fres = fexp2(-dl); resc = true;
; #pragma unroll
;                 for (int kb2 = 0; kb2 < 2; ++kb2)
; #pragma unroll
;                     for (int r = 0; r < 16; ++r) s[kb2][r] -= dl;
;             }
;             float ps = 0.f;
;             v_wait(va);
;             __builtin_amdgcn_s_setprio(1);
; #pragma unroll
;             for (int ks = 0; ks < 4; ++ks) o[0] = MFMA32(v_build(va, ks), pf_[ks], o[0]);
.LaA_loop:
	s_cmp_lt_u32 s14, s13
	s_cbranch_scc0 .LaA_pvonly
	s_and_b32 s6, s14, 3
	s_lshl_b32 s6, s6, 15
	s_add_i32 s7, s14, -1
	s_and_b32 s7, s7, 3
	s_lshl_b32 s7, s7, 15
	v_add_u32_e32 v248, s6, v200
	v_add_u32_e32 v249, s6, v201
	v_add_u32_e32 v250, s6, v202
	v_add_u32_e32 v251, s6, v203
	v_add_u32_e32 v237, s7, v204
	ds_read_b128 v[100:103], v248
	ds_read_b128 v[104:107], v248 offset:4096
	ds_read_b128 v[108:111], v249
	ds_read_b128 v[112:115], v249 offset:4096
	ds_read_b128 v[116:119], v250
	ds_read_b128 v[120:123], v250 offset:4096
	ds_read_b128 v[124:127], v251
	ds_read_b128 v[128:131], v251 offset:4096
	s_cmp_lt_u32 s24, s12
	s_cbranch_scc0 .LaA_nodma_7
	s_and_b32 s6, s24, 3
	s_lshl_b32 s6, s6, 15
	s_add_i32 s7, s6, s22
	s_mov_b32 m0, s7
	s_add_u32 s20, s16, 0x80
	s_addc_u32 s21, s17, 0
	s_add_i32 s29, s6, s23
	global_load_lds_dwordx4 v197, s[16:17]
	s_add_i32 m0, s7, 0x2000
	s_add_u32 s16, s16, 0x20000
	s_addc_u32 s17, s17, 0
	s_nop 0
	global_load_lds_dwordx4 v197, s[20:21]
	s_mov_b32 m0, s29
	s_nop 0
	s_add_u32 s20, s18, 0x80
	s_addc_u32 s21, s19, 0
	s_nop 0
	global_load_lds_dwordx4 v198, s[18:19]
	s_add_i32 m0, s29, 0x400
	s_add_u32 s18, s18, 0x20000
	s_addc_u32 s19, s19, 0
	s_add_i32 s24, s24, 1
	global_load_lds_dwordx4 v198, s[20:21]
.LaA_nodma_7:
	s_waitcnt lgkmcnt(7)
	s_nop 0
	v_mfma_f32_32x32x16_bf16 v[68:83], v[100:103], v[164:167], v[220:235]
	ds_read_b64_tr_b16 v[132:133], v237 offset:0
	ds_read_b64_tr_b16 v[134:135], v237 offset:2048
	s_waitcnt lgkmcnt(8)
	s_nop 0
	v_mfma_f32_32x32x16_bf16 v[84:99], v[104:107], v[164:167], v[220:235]
	ds_read_b64_tr_b16 v[136:137], v237 offset:4096
	ds_read_b64_tr_b16 v[138:139], v237 offset:6144
	s_waitcnt lgkmcnt(9)
	s_nop 0
	v_mfma_f32_32x32x16_bf16 v[68:83], v[108:111], v[168:171], v[68:83]
	ds_read_b64_tr_b16 v[140:141], v237 offset:8192
	ds_read_b64_tr_b16 v[142:143], v237 offset:10240
	s_waitcnt lgkmcnt(10)
	s_nop 0
	v_mfma_f32_32x32x16_bf16 v[84:99], v[112:115], v[168:171], v[84:99]
	ds_read_b64_tr_b16 v[144:145], v237 offset:12288
	ds_read_b64_tr_b16 v[146:147], v237 offset:14336
	s_waitcnt lgkmcnt(11)
	s_nop 0
	v_mfma_f32_32x32x16_bf16 v[68:83], v[116:119], v[172:175], v[68:83]
	s_waitcnt lgkmcnt(10)
	s_nop 0
	v_mfma_f32_32x32x16_bf16 v[84:99], v[120:123], v[172:175], v[84:99]
	s_waitcnt lgkmcnt(9)
	s_nop 0
	v_mfma_f32_32x32x16_bf16 v[68:83], v[124:127], v[176:179], v[68:83]
	s_waitcnt lgkmcnt(8)
	s_nop 0
	v_mfma_f32_32x32x16_bf16 v[84:99], v[128:131], v[176:179], v[84:99]
	s_waitcnt lgkmcnt(0)
	s_nop 0
	ds_read_b64_tr_b16 v[148:149], v237 offset:512
	ds_read_b64_tr_b16 v[150:151], v237 offset:2560
	v_mfma_f32_32x32x16_bf16 v[4:19], v[132:135], v[180:183], v[4:19]
	ds_read_b64_tr_b16 v[152:153], v237 offset:4608
	ds_read_b64_tr_b16 v[154:155], v237 offset:6656
	ds_read_b64_tr_b16 v[156:157], v237 offset:8704
	v_mfma_f32_32x32x16_bf16 v[4:19], v[136:139], v[184:187], v[4:19]
	ds_read_b64_tr_b16 v[158:159], v237 offset:10752
	ds_read_b64_tr_b16 v[160:161], v237 offset:12800
	ds_read_b64_tr_b16 v[162:163], v237 offset:14848
	v_mfma_f32_32x32x16_bf16 v[4:19], v[140:143], v[188:191], v[4:19]
	v_mfma_f32_32x32x16_bf16 v[4:19], v[144:147], v[192:195], v[4:19]
	s_lshl_b32 s6, s14, 6
	s_cmp_gt_i32 s6, s26
	s_cbranch_scc1 .LaA_near_8
.LaA_far_9:
	s_waitcnt lgkmcnt(0)
	ds_read_b64_tr_b16 v[132:133], v237 offset:1024
	ds_read_b64_tr_b16 v[134:135], v237 offset:3072
	v_mfma_f32_32x32x16_bf16 v[20:35], v[148:151], v[180:183], v[20:35]
	ds_read_b64_tr_b16 v[136:137], v237 offset:5120
	ds_read_b64_tr_b16 v[138:139], v237 offset:7168
	ds_read_b64_tr_b16 v[140:141], v237 offset:9216
	v_max_f32_e32 v242, v68, v69
	v_max_f32_e32 v243, v84, v85
	v_max3_f32 v242, v242, v70, v71
	v_max3_f32 v243, v243, v86, v87
	v_max3_f32 v242, v242, v72, v73
	v_mfma_f32_32x32x16_bf16 v[20:35], v[152:155], v[184:187], v[20:35]
	ds_read_b64_tr_b16 v[142:143], v237 offset:11264
	ds_read_b64_tr_b16 v[144:145], v237 offset:13312
	ds_read_b64_tr_b16 v[146:147], v237 offset:15360
	v_max3_f32 v243, v243, v88, v89
	v_max3_f32 v242, v242, v74, v75
	v_max3_f32 v243, v243, v90, v91
	v_max3_f32 v242, v242, v76, v77
	v_max3_f32 v243, v243, v92, v93
	v_mfma_f32_32x32x16_bf16 v[20:35], v[156:159], v[188:191], v[20:35]
	v_max3_f32 v242, v242, v78, v79
	v_max3_f32 v243, v243, v94, v95
	v_max3_f32 v242, v242, v80, v81
	v_max3_f32 v243, v243, v96, v97
	v_max3_f32 v242, v242, v82, v83
	v_mfma_f32_32x32x16_bf16 v[20:35], v[160:163], v[192:195], v[20:35]
	v_max3_f32 v243, v243, v98, v99
	v_max_f32_e32 v242, v242, v243
	v_mov_b32_e32 v243, v242
	s_nop 1
	v_permlane32_swap_b32 v243, v242
	v_max_f32_e64 v247, v243, v242
	v_cmp_lt_f32_e32 vcc, 0x41000000, v247
	s_cmp_lg_u64 vcc, 0
	s_cbranch_scc1 .LaA_resc_pre
; #define MFMA32(a, b, c) __builtin_amdgcn_mfma_f32_32x32x16_bf16((a), (b), (c), 0, 0, 0)
; __device__ __forceinline__ bf16x8 v_build(const VRaw& r, int ks) { return (bf16x8){r.lo[ks][0], r.lo[ks][1], r.lo[ks][2], r.lo[ks][3], r.hv[ks][0], r.hv[ks][1], r.hv[ks][2], r.hv[ks][3]}; }
; #define SB_ __builtin_amdgcn_sched_barrier(0)
; #define EX4_(S, B) do { S[B] = fexp2(S[B]); S[B + 1] = fexp2(S[B + 1]); S[B + 2] = fexp2(S[B + 2]); S[B + 3] = fexp2(S[B + 3]); } while (0)
; #define SUM8_(S, B) do { ps += ((S[B] + S[B + 1]) + (S[B + 2] + S[B + 3])) + ((S[B + 4] + S[B + 5]) + (S[B + 6] + S[B + 7])); } while (0)
; __device__ __forceinline__ void attnA_unit(const P2Ctx& C, int b, int h, int qb) {
;     ...
;             float ps = 0.f;
;             v_wait(va);
;             __builtin_amdgcn_s_setprio(1);
; #pragma unroll
;             for (int ks = 0; ks < 4; ++ks) o[0] = MFMA32(v_build(va, ks), pf_[ks], o[0]);
;             EX4_(s[0], 0); EX4_(s[0], 4); EX4_(s[0], 8); EX4_(s[0], 12);
;             SB_; v_issue<4>(vimg, 1, lane, va); v_wait(va);
; #pragma unroll
;             for (int ks = 0; ks < 4; ++ks) o[1] = MFMA32(v_build(va, ks), pf_[ks], o[1]);
;             EX4_(s[1], 0); EX4_(s[1], 4); EX4_(s[1], 8); EX4_(s[1], 12);
;             SB_; v_issue<4>(vimg, 2, lane, va); v_wait(va);
; #pragma unroll
;             for (int ks = 0; ks < 4; ++ks) o[2] = MFMA32(v_build(va, ks), pf_[ks], o[2]);
;             SUM8_(s[0], 0); SUM8_(s[0], 8); SUM8_(s[1], 0); SUM8_(s[1], 8);
;             SB_; v_issue<4>(vimg, 3, lane, va); v_wait(va);
;             o[3] = MFMA32(v_build(va, 0), pf_[0], o[3]); pf_[0] = pack_p(s[0], 0);
;             o[3] = MFMA32(v_build(va, 1), pf_[1], o[3]); pf_[1] = pack_p(s[0], 1);
;             o[3] = MFMA32(v_build(va, 2), pf_[2], o[3]); pf_[2] = pack_p(s[1], 0);
;             o[3] = MFMA32(v_build(va, 3), pf_[3], o[3]); pf_[3] = pack_p(s[1], 1);
;             __builtin_amdgcn_s_setprio(0);
;             if (resc) {
;                 l *= fres;
; #pragma unroll
;                 for (int cb = 0; cb < 4; ++cb)
; #pragma unroll
;                     for (int r = 0; r < 16; ++r) o[cb][r] *= fres;
;             }
;             l += ps;
.LaA_resc_back:
	s_waitcnt lgkmcnt(0)
	s_nop 0
	ds_read_b64_tr_b16 v[148:149], v237 offset:1536
	ds_read_b64_tr_b16 v[150:151], v237 offset:3584
	v_mfma_f32_32x32x16_bf16 v[36:51], v[132:135], v[180:183], v[36:51]
	ds_read_b64_tr_b16 v[152:153], v237 offset:5632
	ds_read_b64_tr_b16 v[154:155], v237 offset:7680
	ds_read_b64_tr_b16 v[156:157], v237 offset:9728
	v_exp_f32_e32 v68, v68
	v_exp_f32_e32 v69, v69
	v_exp_f32_e32 v70, v70
	v_exp_f32_e32 v71, v71
	v_mfma_f32_32x32x16_bf16 v[36:51], v[136:139], v[184:187], v[36:51]
	ds_read_b64_tr_b16 v[158:159], v237 offset:11776
	ds_read_b64_tr_b16 v[160:161], v237 offset:13824
	ds_read_b64_tr_b16 v[162:163], v237 offset:15872
	v_exp_f32_e32 v72, v72
	v_exp_f32_e32 v73, v73
	v_exp_f32_e32 v74, v74
	v_exp_f32_e32 v75, v75
	v_mfma_f32_32x32x16_bf16 v[36:51], v[140:143], v[188:191], v[36:51]
	v_exp_f32_e32 v76, v76
	v_exp_f32_e32 v77, v77
	v_exp_f32_e32 v78, v78
	v_exp_f32_e32 v79, v79
	v_mfma_f32_32x32x16_bf16 v[36:51], v[144:147], v[192:195], v[36:51]
	v_exp_f32_e32 v80, v80
	v_exp_f32_e32 v81, v81
	v_exp_f32_e64 v82, v82
	v_exp_f32_e32 v83, v83
	s_waitcnt lgkmcnt(0)
	v_mfma_f32_32x32x16_bf16 v[52:67], v[148:151], v[180:183], v[52:67]
	v_exp_f32_e32 v84, v84
	v_exp_f32_e32 v85, v85
	v_exp_f32_e32 v86, v86
	v_exp_f32_e32 v87, v87
	v_exp_f32_e32 v88, v88
	v_exp_f32_e32 v89, v89
	v_exp_f32_e32 v90, v90
	v_exp_f32_e32 v91, v91
	v_cvt_pk_bf16_f32 v180, v68, v69
	v_cvt_pk_bf16_f32 v181, v70, v71
	v_cvt_pk_bf16_f32 v182, v72, v73
	v_cvt_pk_bf16_f32 v183, v74, v75
	v_mfma_f32_32x32x16_bf16 v[52:67], v[152:155], v[184:187], v[52:67]
	v_exp_f32_e32 v92, v92
	v_exp_f32_e32 v93, v93
	v_exp_f32_e32 v94, v94
	v_exp_f32_e32 v95, v95
	v_exp_f32_e32 v96, v96
	v_exp_f32_e32 v97, v97
	v_exp_f32_e32 v98, v98
	v_exp_f32_e32 v99, v99
	v_cvt_pk_bf16_f32 v184, v76, v77
	v_cvt_pk_bf16_f32 v185, v78, v79
	v_cvt_pk_bf16_f32 v186, v80, v81
	v_cvt_pk_bf16_f32 v187, v82, v83
	v_mfma_f32_32x32x16_bf16 v[52:67], v[156:159], v[188:191], v[52:67]
	v_add_f32_e32 v245, v68, v69
	v_add_f32_e32 v243, v70, v71
	v_add_f32_e32 v245, v245, v243
	v_add_f32_e32 v243, v72, v73
	v_add_f32_e32 v242, v74, v75
	v_add_f32_e32 v243, v243, v242
	v_add_f32_e32 v245, v245, v243
	v_add_f32_e32 v246, v76, v77
	v_add_f32_e32 v243, v78, v79
	v_add_f32_e32 v246, v246, v243
	v_add_f32_e32 v243, v80, v81
	v_add_f32_e32 v242, v82, v83
	v_add_f32_e32 v243, v243, v242
	v_add_f32_e32 v246, v246, v243
	v_add_f32_e64 v245, v245, v246
	v_cvt_pk_bf16_f32 v188, v84, v85
	v_cvt_pk_bf16_f32 v189, v86, v87
	v_cvt_pk_bf16_f32 v190, v88, v89
	v_cvt_pk_bf16_f32 v191, v90, v91
	v_mfma_f32_32x32x16_bf16 v[52:67], v[160:163], v[192:195], v[52:67]
	v_add_f32_e32 v246, v84, v85
	v_add_f32_e32 v243, v86, v87
	v_add_f32_e32 v246, v246, v243
	v_add_f32_e32 v243, v88, v89
	v_add_f32_e32 v242, v90, v91
	v_add_f32_e32 v243, v243, v242
	v_add_f32_e32 v246, v246, v243
	v_add_f32_e32 v245, v245, v246
	v_add_f32_e32 v246, v92, v93
	v_add_f32_e32 v243, v94, v95
	v_add_f32_e32 v246, v246, v243
	v_add_f32_e32 v243, v96, v97
	v_add_f32_e32 v242, v98, v99
	v_add_f32_e32 v243, v243, v242
	v_add_f32_e32 v246, v246, v243
	v_add_f32_e32 v245, v245, v246
	v_cvt_pk_bf16_f32 v192, v92, v93
	v_cvt_pk_bf16_f32 v193, v94, v95
	v_cvt_pk_bf16_f32 v194, v96, v97
	v_cvt_pk_bf16_f32 v195, v98, v99
	s_cmp_lg_u32 s25, 0
	s_cbranch_scc1 .LaA_resc_post

; #define LAS __attribute__((address_space(3)))
; __device__ __forceinline__ void attnA_unit(const P2Ctx& C, int b, int h, int qb) {
;     ...
;     l += __shfl_xor(l, 32);
;     const float inv = 1.0f / l;
;     LAS float* X2 = (LAS float*)(lds + 65536);
;     if (comp == 1) {
; #pragma unroll
;         for (int cb = 0; cb < 4; ++cb)
; #pragma unroll
;             for (int r = 0; r < 16; ++r) X2[((qs * 4 + cb) * 16 + r) * 64 + lane] = o[cb][r] * inv;
;     }
;     __syncthreads();
.LaA_nofinalpv_14:
	s_waitcnt lgkmcnt(0)
	s_barrier
	v_mov_b32_e32 v243, v241
	s_nop 1
	v_permlane32_swap_b32 v243, v241
	v_add_f32_e32 v241, v243, v241
	v_rcp_f32_e32 v241, v241
	s_lshl_b32 s6, s9, 14
	s_add_i32 s6, s6, 0x10000
	v_lshlrev_b32_e32 v2, 2, v219
	v_add_u32_e32 v2, s6, v2
	s_cmp_eq_u32 s8, 0
	s_cbranch_scc1 .LaA_comp0_15
	s_nop 7
	s_nop 3
	v_mul_f32_e32 v68, v4, v241
	ds_write_b32 v2, v68 offset:0
	v_mul_f32_e32 v69, v5, v241
	ds_write_b32 v2, v69 offset:256
	v_mul_f32_e32 v68, v6, v241
	ds_write_b32 v2, v68 offset:512
	v_mul_f32_e32 v69, v7, v241
	ds_write_b32 v2, v69 offset:768
	v_mul_f32_e32 v68, v8, v241
	ds_write_b32 v2, v68 offset:1024
	v_mul_f32_e32 v69, v9, v241
	ds_write_b32 v2, v69 offset:1280
	v_mul_f32_e32 v68, v10, v241
	ds_write_b32 v2, v68 offset:1536
	v_mul_f32_e32 v69, v11, v241
	ds_write_b32 v2, v69 offset:1792
	v_mul_f32_e32 v68, v12, v241
	ds_write_b32 v2, v68 offset:2048
	v_mul_f32_e32 v69, v13, v241
	ds_write_b32 v2, v69 offset:2304
	v_mul_f32_e32 v68, v14, v241
	ds_write_b32 v2, v68 offset:2560
	v_mul_f32_e32 v69, v15, v241
	ds_write_b32 v2, v69 offset:2816
	v_mul_f32_e32 v68, v16, v241
	ds_write_b32 v2, v68 offset:3072
	v_mul_f32_e32 v69, v17, v241
	ds_write_b32 v2, v69 offset:3328
	v_mul_f32_e32 v68, v18, v241
	ds_write_b32 v2, v68 offset:3584
	v_mul_f32_e32 v69, v19, v241
	ds_write_b32 v2, v69 offset:3840
	v_mul_f32_e32 v68, v20, v241
	ds_write_b32 v2, v68 offset:4096
	v_mul_f32_e32 v69, v21, v241
	ds_write_b32 v2, v69 offset:4352
	v_mul_f32_e32 v68, v22, v241
	ds_write_b32 v2, v68 offset:4608
	v_mul_f32_e32 v69, v23, v241
	ds_write_b32 v2, v69 offset:4864
	v_mul_f32_e32 v68, v24, v241
	ds_write_b32 v2, v68 offset:5120
	v_mul_f32_e32 v69, v25, v241
	ds_write_b32 v2, v69 offset:5376
	v_mul_f32_e32 v68, v26, v241
	ds_write_b32 v2, v68 offset:5632
	v_mul_f32_e32 v69, v27, v241
	ds_write_b32 v2, v69 offset:5888
	v_mul_f32_e32 v68, v28, v241
	ds_write_b32 v2, v68 offset:6144
	v_mul_f32_e32 v69, v29, v241
	ds_write_b32 v2, v69 offset:6400
	v_mul_f32_e32 v68, v30, v241
	ds_write_b32 v2, v68 offset:6656
	v_mul_f32_e32 v69, v31, v241
	ds_write_b32 v2, v69 offset:6912
	v_mul_f32_e32 v68, v32, v241
	ds_write_b32 v2, v68 offset:7168
	v_mul_f32_e32 v69, v33, v241
	ds_write_b32 v2, v69 offset:7424
	v_mul_f32_e32 v68, v34, v241
	ds_write_b32 v2, v68 offset:7680
	v_mul_f32_e32 v69, v35, v241
	ds_write_b32 v2, v69 offset:7936
	v_mul_f32_e32 v68, v36, v241
	ds_write_b32 v2, v68 offset:8192
	v_mul_f32_e32 v69, v37, v241
	ds_write_b32 v2, v69 offset:8448
	v_mul_f32_e32 v68, v38, v241
	ds_write_b32 v2, v68 offset:8704
	v_mul_f32_e32 v69, v39, v241
	ds_write_b32 v2, v69 offset:8960
	v_mul_f32_e32 v68, v40, v241
	ds_write_b32 v2, v68 offset:9216
	v_mul_f32_e32 v69, v41, v241
	ds_write_b32 v2, v69 offset:9472
	v_mul_f32_e32 v68, v42, v241
	ds_write_b32 v2, v68 offset:9728
	v_mul_f32_e32 v69, v43, v241
	ds_write_b32 v2, v69 offset:9984
	v_mul_f32_e32 v68, v44, v241
	ds_write_b32 v2, v68 offset:10240
	v_mul_f32_e32 v69, v45, v241
	ds_write_b32 v2, v69 offset:10496
	v_mul_f32_e32 v68, v46, v241
	ds_write_b32 v2, v68 offset:10752
	v_mul_f32_e32 v69, v47, v241
	ds_write_b32 v2, v69 offset:11008
	v_mul_f32_e32 v68, v48, v241
	ds_write_b32 v2, v68 offset:11264
	v_mul_f32_e32 v69, v49, v241
	ds_write_b32 v2, v69 offset:11520
	v_mul_f32_e32 v68, v50, v241
	ds_write_b32 v2, v68 offset:11776
	v_mul_f32_e32 v69, v51, v241
	ds_write_b32 v2, v69 offset:12032
	v_mul_f32_e32 v68, v52, v241
	ds_write_b32 v2, v68 offset:12288
	v_mul_f32_e32 v69, v53, v241
	ds_write_b32 v2, v69 offset:12544
	v_mul_f32_e32 v68, v54, v241
	ds_write_b32 v2, v68 offset:12800
	v_mul_f32_e32 v69, v55, v241
	ds_write_b32 v2, v69 offset:13056
	v_mul_f32_e32 v68, v56, v241
	ds_write_b32 v2, v68 offset:13312
	v_mul_f32_e32 v69, v57, v241
	ds_write_b32 v2, v69 offset:13568
	v_mul_f32_e32 v68, v58, v241
	ds_write_b32 v2, v68 offset:13824
	v_mul_f32_e32 v69, v59, v241
	ds_write_b32 v2, v69 offset:14080
	v_mul_f32_e32 v68, v60, v241
	ds_write_b32 v2, v68 offset:14336
	v_mul_f32_e32 v69, v61, v241
	ds_write_b32 v2, v69 offset:14592
	v_mul_f32_e32 v68, v62, v241
	ds_write_b32 v2, v68 offset:14848
	v_mul_f32_e32 v69, v63, v241
	ds_write_b32 v2, v69 offset:15104
	v_mul_f32_e32 v68, v64, v241
	ds_write_b32 v2, v68 offset:15360
	v_mul_f32_e32 v69, v65, v241
	ds_write_b32 v2, v69 offset:15616
	v_mul_f32_e32 v68, v66, v241
	ds_write_b32 v2, v68 offset:15872
	v_mul_f32_e32 v69, v67, v241
	ds_write_b32 v2, v69 offset:16128
	s_waitcnt lgkmcnt(0)
	s_barrier
	s_branch .LaA_epiend_16
; __device__ __forceinline__ void attnA_unit(const P2Ctx& C, int b, int h, int qb) {
;     ...
;     if (comp == 1) {
; #pragma unroll
;         for (int cb = 0; cb < 4; ++cb)
; #pragma unroll
;             for (int r = 0; r < 16; ++r) X2[((qs * 4 + cb) * 16 + r) * 64 + lane] = o[cb][r] * inv;
;     }
;     __syncthreads();
;     if (comp == 0) {
; #pragma unroll
;         for (int cb = 0; cb < 4; ++cb)
; #pragma unroll
;             for (int r = 0; r < 16; ++r) o[cb][r] = o[cb][r] * inv - lam * X2[((qs * 4 + cb) * 16 + r) * 64 + lane];
;         subln_store(o, C.a->in[I_SUBG], C.AO + qrow * DM + h * 128, lane);
;     }
	s_nop 0
	s_nop 0
	s_nop 0
	s_nop 0
	s_nop 0
	s_nop 0
	s_nop 0
	s_nop 0
	s_nop 0
	s_nop 0
	s_nop 0
	s_nop 0
	s_nop 0
	s_nop 0
	s_nop 0
	s_nop 0
	s_nop 0
	s_nop 0
	s_nop 0
	s_nop 0
	s_nop 0
	s_nop 0
	s_nop 0
	s_nop 0
	s_nop 0
	s_nop 0
	s_nop 0
	s_nop 0
	s_nop 0
	s_nop 0
	s_nop 0
	s_nop 0
	s_nop 0
	s_nop 0
	s_nop 0
	s_nop 0
	s_nop 0
	s_nop 0
	s_nop 0
	s_nop 0
	s_nop 0
	s_nop 0
	s_nop 0
	s_nop 0
	s_nop 0
	s_nop 0
	s_nop 0
	s_nop 0
	s_nop 0
	s_nop 0
	s_nop 0
	s_nop 0
	s_nop 0
	s_nop 0
	s_nop 0
	s_nop 0
	s_nop 0
	s_nop 0
	s_nop 0
	s_nop 0
	s_nop 0
	s_nop 0
	s_nop 0
	s_nop 0
	s_nop 0
	s_nop 0
	s_nop 0
	s_nop 0
	s_nop 0
	s_nop 0
	s_nop 0
	s_nop 0
	s_nop 0
	s_nop 0
	s_nop 0
	s_nop 0
	s_nop 0
	s_nop 0
	s_nop 0
	s_nop 0
	s_nop 0
	s_nop 0
	s_nop 0
	s_nop 0
	s_nop 0
	s_nop 0
	s_nop 0
	s_nop 0
	s_nop 0
	s_nop 0
	s_nop 0
	s_nop 0
	s_nop 0
	s_nop 0
	s_nop 0
	s_nop 0
	s_nop 0
	s_nop 0
	s_nop 0
	s_nop 0
	s_nop 0
	s_nop 0
	s_nop 0
	s_nop 0
	s_nop 0
	s_nop 0
	s_nop 0
	s_nop 0
	s_nop 0
	s_nop 0
	s_nop 0
	s_nop 0
	s_nop 0
	s_nop 0
	s_nop 0
	s_nop 0
	s_nop 0
	s_nop 0
	s_nop 0
	s_nop 0
	s_nop 0
	s_nop 0
	s_nop 0
	s_nop 0
	s_nop 0
	s_nop 0
	s_nop 0
	s_nop 0
	s_nop 0
	s_nop 0
	s_nop 0
	s_nop 0
	s_nop 0
	s_nop 0
	s_nop 0
	s_nop 0
	s_nop 0
	s_nop 0
	s_nop 0
	s_nop 0
	s_nop 0
	s_nop 0
	s_nop 0
	s_nop 0
	s_nop 0
	s_nop 0
	s_nop 0
	s_nop 0
	s_nop 0
	s_nop 0
	s_nop 0
	s_nop 0
	s_nop 0
	s_nop 0
	s_nop 0
	s_nop 0
	s_nop 0
	s_nop 0
	s_nop 0
	s_nop 0
	s_nop 0
	s_nop 0
	s_nop 0
	s_nop 0
	s_nop 0
	s_nop 0
	s_nop 0
	s_nop 0
	s_nop 0
	s_nop 0
	s_nop 0
	s_nop 0
	s_nop 0
	s_nop 0
	s_nop 0
	s_nop 0
	s_nop 0
	s_nop 0
	s_nop 0
	s_nop 0
	s_nop 0
	s_nop 0
	s_nop 0
	s_nop 0
	s_nop 0
	s_nop 0
	s_nop 0
	s_nop 0
	s_nop 0
	s_nop 0
	s_nop 0
	s_nop 0
	s_nop 0
	s_nop 0
	s_nop 0
	s_nop 0
	s_nop 0
	s_nop 0
	s_nop 0
	s_nop 0
	s_nop 0
	s_nop 0
	s_nop 0
	s_nop 0
	s_nop 0
	s_nop 0
	s_nop 0
	s_nop 0
	s_nop 0
	s_nop 0
	s_nop 0
	s_nop 0
	s_nop 0
	s_nop 0
	s_nop 0
	s_nop 0
	s_nop 0
	s_nop 0
	s_nop 0
	s_nop 0
	s_nop 0
	s_nop 0
	s_nop 0
	s_nop 0
	s_nop 0
	s_nop 0
	s_nop 0
	s_nop 0
	s_nop 0
	s_nop 0
	s_nop 0
	s_nop 0
	s_nop 0
	s_nop 0
	s_nop 0
	s_nop 0
	s_nop 0
	s_nop 0
	s_nop 0
	s_nop 0
	s_nop 0
	s_nop 0
	s_nop 0
	s_nop 0
	s_nop 0
	s_nop 0
	s_nop 0
	s_nop 0
	s_nop 0
	s_nop 0
	s_nop 0
	s_nop 0
	s_nop 0
	s_nop 0
	s_nop 0
	s_nop 0
	s_nop 0
	s_nop 0
	s_nop 0
	s_nop 0
	s_nop 0
	s_nop 0
	s_nop 0
	s_nop 0
	s_nop 0
	s_nop 0
	s_nop 0
	s_nop 0
	s_nop 0
	s_nop 0
	s_nop 0
	s_nop 0
	s_nop 0
	s_nop 0
	s_nop 0
	s_nop 0
	s_nop 0
	s_nop 0
	s_nop 0
	s_nop 0
	s_nop 0
	s_nop 0
	s_nop 0
	s_nop 0
	s_nop 0
	s_nop 0
	s_nop 0
	s_nop 0
	s_nop 0
	s_nop 0
	s_nop 0
	s_nop 0
	s_nop 0
	s_nop 0
	s_nop 0
	s_nop 0
	s_nop 0
	s_nop 0
	s_nop 0
	s_nop 0
	s_nop 0
	s_nop 0
	s_nop 0
	s_nop 0
	s_nop 0
	s_nop 0
	s_nop 0
	s_nop 0
	s_nop 0
	s_nop 0
	s_nop 0
	s_nop 0
	s_nop 0
	s_nop 0
	s_nop 0
	s_nop 0
	s_nop 0
	s_nop 0
	s_nop 0
	s_nop 0
	s_nop 0
	s_nop 0
	s_nop 0
	s_nop 0
	s_nop 0
	s_nop 0
	s_nop 0
	s_nop 0
	s_nop 0
	s_nop 0
	s_nop 0
	s_nop 0
	s_nop 0
	s_nop 0
	s_nop 0
	s_nop 0
	s_nop 0
	s_nop 0
	s_nop 0
	s_nop 0
	s_nop 0
	s_nop 0
	s_nop 0
	s_nop 0
	s_nop 0
	s_nop 0
	s_nop 0
	s_nop 0
	s_nop 0
	s_nop 0
	s_nop 0
	s_nop 0
	s_nop 0
	s_nop 0
	s_nop 0
	s_nop 0
	s_nop 0
	s_nop 0
	s_nop 0
	s_nop 0
	s_nop 0
	s_nop 0
	s_nop 0
	s_nop 0
	s_nop 0
	s_nop 0
	s_nop 0
	s_nop 0
	s_nop 0
	s_nop 0
	s_nop 0
	s_nop 0
	s_nop 0
	s_nop 0
	s_nop 0
	s_nop 0
	s_nop 0
	s_nop 0
	s_nop 0
	s_nop 0
	s_nop 0
	s_nop 0
	s_nop 0
	s_nop 0
	s_nop 0
	s_nop 0
	s_nop 0
	s_nop 0
	s_nop 0
	s_nop 0
	s_nop 0
	s_nop 0
	s_nop 0
	s_nop 0
	s_nop 0
	s_nop 0
	s_nop 0
	s_nop 0
	s_nop 0
	s_nop 0
	s_nop 0
	s_nop 0
	s_nop 0
	s_nop 0
	s_nop 0
	s_nop 0
	s_nop 0
	s_nop 0
	s_nop 0
	s_nop 0
	s_nop 0
	s_nop 0
	s_nop 0
	s_nop 0
	s_nop 0
	s_nop 0
	s_nop 0
	s_nop 0
	s_nop 0
	s_nop 0
	s_nop 0
	s_nop 0
	s_nop 0
	s_nop 0
	s_nop 0
	s_nop 0
	s_nop 0
	s_nop 0
	s_nop 0
	s_nop 0
	s_nop 0
	s_nop 0
	s_nop 0
	s_nop 0
	s_nop 0
	s_nop 0
	s_nop 0
	s_nop 0
	s_nop 0
	s_nop 0
	s_nop 0
	s_nop 0
	s_nop 0
	s_nop 0
	s_nop 0
	s_nop 0
	s_nop 0
	s_nop 0
	s_nop 0
	s_nop 0
	s_nop 0
	s_nop 0
	s_nop 0
	s_nop 0
	s_nop 0
	s_nop 0
	s_nop 0
	s_nop 0
	s_nop 0
	s_nop 0
	s_nop 0
	s_nop 0
	s_nop 0
	s_nop 0
	s_nop 0
	s_nop 0
	s_nop 0
	s_nop 0
	s_nop 0
	s_nop 0
	s_nop 0
	s_nop 0
	s_nop 0
	s_nop 0
	s_nop 0
	s_nop 0
	s_nop 0
	s_nop 0
	s_nop 0
	s_nop 0
	s_nop 0
	s_nop 0
	s_nop 0
	s_nop 0
	s_nop 0
	s_nop 0
	s_nop 0
	s_nop 0
	s_nop 0
	s_nop 0
	s_nop 0
	s_nop 0
	s_nop 0
	s_nop 0
	s_nop 0
	s_nop 0
	s_nop 0
	s_nop 0
	s_nop 0
	s_nop 0
	s_nop 0
	s_nop 0
	s_nop 0
	s_nop 0
	s_nop 0
	s_nop 0
	s_nop 0
	s_nop 0
	s_nop 0
	s_nop 0
	s_nop 0
	s_nop 0
	s_nop 0
	s_nop 0
	s_nop 0
	s_nop 0
	s_nop 0
	s_nop 0
	s_nop 0
	s_nop 0
	s_nop 0
	s_nop 0
	s_nop 0
	s_nop 0
	s_nop 0
	s_nop 0
	s_nop 0
	s_nop 0
	s_nop 0
	s_nop 0
	s_nop 0
	s_nop 0
	s_nop 0
	s_nop 0
	s_nop 0
	s_nop 0
	s_nop 0
	s_nop 0
	s_nop 0
	s_nop 0
	s_nop 0
	s_nop 0
	s_nop 0
	s_nop 0
	s_nop 0
	s_nop 0
	s_nop 0
	s_nop 0
	s_nop 0
	s_nop 0
	s_nop 0
	s_nop 0
	s_nop 0
	s_nop 0
	s_nop 0
	s_nop 0
	s_nop 0
	s_nop 0
	s_nop 0
	s_nop 0
	s_nop 0
	s_nop 0
	s_nop 0
	s_nop 0
	s_nop 0
	s_nop 0
	s_nop 0
	s_nop 0
	s_nop 0
	s_nop 0
	s_nop 0
	s_nop 0
	s_nop 0
	s_nop 0
	s_nop 0
	s_nop 0
	s_nop 0
	s_nop 0
	s_nop 0
	s_nop 0
	s_nop 0
	s_nop 0
	s_nop 0
	s_nop 0
	s_nop 0
	s_nop 0
	s_nop 0
	s_nop 0
	s_nop 0
	s_nop 0
	s_nop 0
	s_nop 0
	s_nop 0
	s_nop 0
	s_nop 0
	s_nop 0
	s_nop 0
	s_nop 0
	s_nop 0
	s_nop 0
	s_nop 0
	s_nop 0
	s_nop 0
	s_nop 0
	s_nop 0
	s_nop 0
	s_nop 0
	s_nop 0
	s_nop 0
	s_nop 0
	s_nop 0
	s_nop 0
	s_nop 0
	s_nop 0
	s_nop 0
	s_nop 0
	s_nop 0
	s_nop 0
	s_nop 0
	s_nop 0
	s_nop 0
	s_nop 0
	s_nop 0
	s_nop 0
	s_nop 0
	s_nop 0
	s_nop 0
	s_nop 0
	s_nop 0
	s_nop 0
	s_nop 0
	s_nop 0
	s_nop 0
	s_nop 0
	s_nop 0
	s_nop 0
	s_nop 0
	s_nop 0
	s_nop 0
	s_nop 0
	s_nop 0
	s_nop 0
	s_nop 0
	s_nop 0
	s_nop 0
	s_nop 0
	s_nop 0
	s_nop 0
	s_nop 0
	s_nop 0
	s_nop 0
	s_nop 0
	s_nop 0
	s_nop 0
	s_nop 0
	s_nop 0
	s_nop 0
	s_nop 0
	s_nop 0
	s_nop 0
	s_nop 0
	s_nop 0
	s_nop 0
	s_nop 0
	s_nop 0
	s_nop 0
	s_nop 0
	s_nop 0
; __device__ __forceinline__ void subln_store(f32x16 (&o)[4], const float* subg, bf16_t* dst  , int lane) {
;     ...
;     f32x4 sg[4][4];
; #pragma unroll
;     for (int cb = 0; cb < 4; ++cb)
; #pragma unroll
;         for (int g = 0; g < 4; ++g) sg[cb][g] = *(const f32x4*)(subg + 32 * cb + 8 * g + 4 * hi);
;     asm volatile("" ::: "memory");
; __device__ __forceinline__ void attnA_unit(const P2Ctx& C, int b, int h, int qb) {
;     ...
;     if (comp == 0) {
; #pragma unroll
;         for (int cb = 0; cb < 4; ++cb)
; #pragma unroll
;             for (int r = 0; r < 16; ++r) o[cb][r] = o[cb][r] * inv - lam * X2[((qs * 4 + cb) * 16 + r) * 64 + lane];
.LaA_comp0_15:
	v_lshrrev_b32_e32 v242, 5, v219
	v_lshlrev_b32_e32 v242, 4, v242
	v_add_u32_e32 v242, 0x22a00, v242
	ds_read_b128 v[100:103], v242 offset:0
	ds_read_b128 v[104:107], v242 offset:32
	ds_read_b128 v[108:111], v242 offset:64
	ds_read_b128 v[112:115], v242 offset:96
	ds_read_b128 v[116:119], v242 offset:128
	ds_read_b128 v[120:123], v242 offset:160
	ds_read_b128 v[124:127], v242 offset:192
	ds_read_b128 v[128:131], v242 offset:224
	s_waitcnt lgkmcnt(4)
	ds_read_b128 v[132:135], v242 offset:256
	ds_read_b128 v[136:139], v242 offset:288
	ds_read_b128 v[140:143], v242 offset:320
	ds_read_b128 v[144:147], v242 offset:352
	ds_read_b128 v[148:151], v242 offset:384
	ds_read_b128 v[152:155], v242 offset:416
	ds_read_b128 v[156:159], v242 offset:448
	ds_read_b128 v[160:163], v242 offset:480
	s_waitcnt lgkmcnt(6)
	ds_read_b32 v243, v207
	s_nop 7
	s_nop 3
	v_mul_f32_e32 v4, v4, v241
	v_mul_f32_e32 v5, v5, v241
	v_mul_f32_e32 v6, v6, v241
	v_mul_f32_e32 v7, v7, v241
	v_mul_f32_e32 v8, v8, v241
	v_mul_f32_e32 v9, v9, v241
	v_mul_f32_e32 v10, v10, v241
	v_mul_f32_e32 v11, v11, v241
	v_mul_f32_e32 v12, v12, v241
	v_mul_f32_e32 v13, v13, v241
	v_mul_f32_e32 v14, v14, v241
	v_mul_f32_e32 v15, v15, v241
	v_mul_f32_e32 v16, v16, v241
	v_mul_f32_e32 v17, v17, v241
	v_mul_f32_e32 v18, v18, v241
	v_mul_f32_e32 v19, v19, v241
	v_mul_f32_e32 v20, v20, v241
	v_mul_f32_e32 v21, v21, v241
	v_mul_f32_e32 v22, v22, v241
	v_mul_f32_e32 v23, v23, v241
	v_mul_f32_e32 v24, v24, v241
	v_mul_f32_e32 v25, v25, v241
	v_mul_f32_e32 v26, v26, v241
	v_mul_f32_e32 v27, v27, v241
	v_mul_f32_e32 v28, v28, v241
	v_mul_f32_e32 v29, v29, v241
	v_mul_f32_e32 v30, v30, v241
	v_mul_f32_e32 v31, v31, v241
	v_mul_f32_e32 v32, v32, v241
	v_mul_f32_e32 v33, v33, v241
	v_mul_f32_e32 v34, v34, v241
	v_mul_f32_e32 v35, v35, v241
	v_mul_f32_e32 v36, v36, v241
	v_mul_f32_e32 v37, v37, v241
	v_mul_f32_e32 v38, v38, v241
	v_mul_f32_e32 v39, v39, v241
	v_mul_f32_e32 v40, v40, v241
	v_mul_f32_e32 v41, v41, v241
	v_mul_f32_e32 v42, v42, v241
	v_mul_f32_e32 v43, v43, v241
	v_mul_f32_e32 v44, v44, v241
	v_mul_f32_e32 v45, v45, v241
	v_mul_f32_e32 v46, v46, v241
	v_mul_f32_e32 v47, v47, v241
	v_mul_f32_e32 v48, v48, v241
	v_mul_f32_e32 v49, v49, v241
	v_mul_f32_e32 v50, v50, v241
	v_mul_f32_e32 v51, v51, v241
	v_mul_f32_e32 v52, v52, v241
	v_mul_f32_e32 v53, v53, v241
	v_mul_f32_e32 v54, v54, v241
	v_mul_f32_e32 v55, v55, v241
	v_mul_f32_e32 v56, v56, v241
	v_mul_f32_e32 v57, v57, v241
	v_mul_f32_e32 v58, v58, v241
	v_mul_f32_e32 v59, v59, v241
	v_mul_f32_e32 v60, v60, v241
	v_mul_f32_e32 v61, v61, v241
	v_mul_f32_e32 v62, v62, v241
	v_mul_f32_e32 v63, v63, v241
	v_mul_f32_e32 v64, v64, v241
	v_mul_f32_e32 v65, v65, v241
	v_mul_f32_e32 v66, v66, v241
	v_mul_f32_e32 v67, v67, v241
	s_waitcnt lgkmcnt(0)
	s_barrier
	ds_read2st64_b32 v[164:165], v2 offset0:0 offset1:1
	ds_read2st64_b32 v[166:167], v2 offset0:2 offset1:3
	ds_read2st64_b32 v[168:169], v2 offset0:4 offset1:5
	ds_read2st64_b32 v[170:171], v2 offset0:6 offset1:7
	ds_read2st64_b32 v[172:173], v2 offset0:8 offset1:9
	ds_read2st64_b32 v[174:175], v2 offset0:10 offset1:11
	ds_read2st64_b32 v[176:177], v2 offset0:12 offset1:13
	ds_read2st64_b32 v[178:179], v2 offset0:14 offset1:15
	ds_read2st64_b32 v[180:181], v2 offset0:16 offset1:17
	ds_read2st64_b32 v[182:183], v2 offset0:18 offset1:19
	ds_read2st64_b32 v[184:185], v2 offset0:20 offset1:21
	ds_read2st64_b32 v[186:187], v2 offset0:22 offset1:23
	ds_read2st64_b32 v[188:189], v2 offset0:24 offset1:25
	ds_read2st64_b32 v[190:191], v2 offset0:26 offset1:27
	ds_read2st64_b32 v[192:193], v2 offset0:28 offset1:29
	s_waitcnt lgkmcnt(8)
	ds_read2st64_b32 v[194:195], v2 offset0:30 offset1:31
	ds_read2st64_b32 v[68:69], v2 offset0:32 offset1:33
	ds_read2st64_b32 v[70:71], v2 offset0:34 offset1:35
	ds_read2st64_b32 v[72:73], v2 offset0:36 offset1:37
	ds_read2st64_b32 v[74:75], v2 offset0:38 offset1:39
	ds_read2st64_b32 v[76:77], v2 offset0:40 offset1:41
	ds_read2st64_b32 v[78:79], v2 offset0:42 offset1:43
	ds_read2st64_b32 v[80:81], v2 offset0:44 offset1:45
	ds_read2st64_b32 v[82:83], v2 offset0:46 offset1:47
	ds_read2st64_b32 v[84:85], v2 offset0:48 offset1:49
	ds_read2st64_b32 v[86:87], v2 offset0:50 offset1:51
	ds_read2st64_b32 v[88:89], v2 offset0:52 offset1:53
	ds_read2st64_b32 v[90:91], v2 offset0:54 offset1:55
	ds_read2st64_b32 v[92:93], v2 offset0:56 offset1:57
	ds_read2st64_b32 v[94:95], v2 offset0:58 offset1:59
	ds_read2st64_b32 v[96:97], v2 offset0:60 offset1:61
	ds_read2st64_b32 v[98:99], v2 offset0:62 offset1:63
	s_waitcnt lgkmcnt(0)
; __device__ __forceinline__ void subln_store(f32x16 (&o)[4], const float* subg, bf16_t* dst  , int lane) {
;     const int hi = lane >> 5;
;     float ss = 0.f;
; #pragma unroll
;     for (int cb = 0; cb < 4; ++cb)
; #pragma unroll
;         for (int r = 0; r < 16; ++r) ss += o[cb][r] * o[cb][r];
;     ss += __shfl_xor(ss, 32);
;     const float rstd = (1.0f - LAMBDA_INIT) / sqrtf(ss * (1.0f / 128.0f) + EPS);
; __device__ __forceinline__ void attnA_unit(const P2Ctx& C, int b, int h, int qb) {
;     ...
;             for (int r = 0; r < 16; ++r) o[cb][r] = o[cb][r] * inv - lam * X2[((qs * 4 + cb) * 16 + r) * 64 + lane];
	v_fma_f32 v4, -v243, v164, v4
	v_fma_f32 v5, -v243, v165, v5
	v_fma_f32 v6, -v243, v166, v6
	v_fma_f32 v7, -v243, v167, v7
	v_fma_f32 v8, -v243, v168, v8
	v_fma_f32 v9, -v243, v169, v9
	v_fma_f32 v10, -v243, v170, v10
	v_fma_f32 v11, -v243, v171, v11
	v_fma_f32 v12, -v243, v172, v12
	v_fma_f32 v13, -v243, v173, v13
	v_fma_f32 v14, -v243, v174, v14
	v_fma_f32 v15, -v243, v175, v15
	v_fma_f32 v16, -v243, v176, v16
	v_fma_f32 v17, -v243, v177, v17
	v_fma_f32 v18, -v243, v178, v18
	v_fma_f32 v19, -v243, v179, v19
	v_fma_f32 v20, -v243, v180, v20
	v_fma_f32 v21, -v243, v181, v21
	v_fma_f32 v22, -v243, v182, v22
	v_fma_f32 v23, -v243, v183, v23
	v_fma_f32 v24, -v243, v184, v24
	v_fma_f32 v25, -v243, v185, v25
	v_fma_f32 v26, -v243, v186, v26
	v_fma_f32 v27, -v243, v187, v27
	v_fma_f32 v28, -v243, v188, v28
	v_fma_f32 v29, -v243, v189, v29
	v_fma_f32 v30, -v243, v190, v30
	v_fma_f32 v31, -v243, v191, v31
	v_fma_f32 v32, -v243, v192, v32
	v_fma_f32 v33, -v243, v193, v33
	v_fma_f32 v34, -v243, v194, v34
	v_fma_f32 v35, -v243, v195, v35
	v_fma_f32 v36, -v243, v68, v36
	v_fma_f32 v37, -v243, v69, v37
	v_fma_f32 v38, -v243, v70, v38
	v_fma_f32 v39, -v243, v71, v39
	v_fma_f32 v40, -v243, v72, v40
	v_fma_f32 v41, -v243, v73, v41
	v_fma_f32 v42, -v243, v74, v42
	v_fma_f32 v43, -v243, v75, v43
	v_fma_f32 v44, -v243, v76, v44
	v_fma_f32 v45, -v243, v77, v45
	v_fma_f32 v46, -v243, v78, v46
	v_fma_f32 v47, -v243, v79, v47
	v_fma_f32 v48, -v243, v80, v48
	v_fma_f32 v49, -v243, v81, v49
	v_fma_f32 v50, -v243, v82, v50
	v_fma_f32 v51, -v243, v83, v51
	v_fma_f32 v52, -v243, v84, v52
	v_fma_f32 v53, -v243, v85, v53
	v_fma_f32 v54, -v243, v86, v54
	v_fma_f32 v55, -v243, v87, v55
	v_fma_f32 v56, -v243, v88, v56
	v_fma_f32 v57, -v243, v89, v57
	v_fma_f32 v58, -v243, v90, v58
	v_fma_f32 v59, -v243, v91, v59
	v_fma_f32 v60, -v243, v92, v60
	v_fma_f32 v61, -v243, v93, v61
	v_fma_f32 v62, -v243, v94, v62
	v_fma_f32 v63, -v243, v95, v63
	v_fma_f32 v64, -v243, v96, v64
	v_fma_f32 v65, -v243, v97, v65
	v_fma_f32 v66, -v243, v98, v66
	v_fma_f32 v67, -v243, v99, v67
	v_mul_f32_e32 v245, v4, v4
	v_fmac_f32_e32 v245, v5, v5
	v_fmac_f32_e32 v245, v6, v6
	v_fmac_f32_e32 v245, v7, v7
	v_fmac_f32_e32 v245, v8, v8
	v_fmac_f32_e32 v245, v9, v9
	v_fmac_f32_e32 v245, v10, v10
	v_fmac_f32_e32 v245, v11, v11
	v_fmac_f32_e32 v245, v12, v12
	v_fmac_f32_e32 v245, v13, v13
	v_fmac_f32_e32 v245, v14, v14
	v_fmac_f32_e32 v245, v15, v15
	v_fmac_f32_e32 v245, v16, v16
	v_fmac_f32_e32 v245, v17, v17
	v_fmac_f32_e32 v245, v18, v18
	v_fmac_f32_e32 v245, v19, v19
	v_fmac_f32_e32 v245, v20, v20
	v_fmac_f32_e32 v245, v21, v21
	v_fmac_f32_e32 v245, v22, v22
	v_fmac_f32_e32 v245, v23, v23
	v_fmac_f32_e32 v245, v24, v24
	v_fmac_f32_e32 v245, v25, v25
	v_fmac_f32_e32 v245, v26, v26
	v_fmac_f32_e32 v245, v27, v27
	v_fmac_f32_e32 v245, v28, v28
	v_fmac_f32_e32 v245, v29, v29
	v_fmac_f32_e32 v245, v30, v30
	v_fmac_f32_e32 v245, v31, v31
	v_fmac_f32_e32 v245, v32, v32
	v_fmac_f32_e32 v245, v33, v33
	v_fmac_f32_e32 v245, v34, v34
	v_fmac_f32_e32 v245, v35, v35
	v_fmac_f32_e32 v245, v36, v36
	v_fmac_f32_e32 v245, v37, v37
	v_fmac_f32_e32 v245, v38, v38
	v_fmac_f32_e32 v245, v39, v39
	v_fmac_f32_e32 v245, v40, v40
	v_fmac_f32_e32 v245, v41, v41
	v_fmac_f32_e32 v245, v42, v42
	v_fmac_f32_e32 v245, v43, v43
	v_fmac_f32_e32 v245, v44, v44
	v_fmac_f32_e32 v245, v45, v45
	v_fmac_f32_e32 v245, v46, v46
	v_fmac_f32_e32 v245, v47, v47
	v_fmac_f32_e32 v245, v48, v48
	v_fmac_f32_e32 v245, v49, v49
	v_fmac_f32_e32 v245, v50, v50
	v_fmac_f32_e32 v245, v51, v51
	v_fmac_f32_e32 v245, v52, v52
	v_fmac_f32_e32 v245, v53, v53
	v_fmac_f32_e32 v245, v54, v54
	v_fmac_f32_e32 v245, v55, v55
	v_fmac_f32_e32 v245, v56, v56
	v_fmac_f32_e32 v245, v57, v57
	v_fmac_f32_e32 v245, v58, v58
	v_fmac_f32_e32 v245, v59, v59
	v_fmac_f32_e32 v245, v60, v60
	v_fmac_f32_e32 v245, v61, v61
	v_fmac_f32_e32 v245, v62, v62
	v_fmac_f32_e32 v245, v63, v63
	v_fmac_f32_e32 v245, v64, v64
	v_fmac_f32_e32 v245, v65, v65
	v_fmac_f32_e32 v245, v66, v66
	v_fmac_f32_e32 v245, v67, v67
	v_mov_b32_e32 v246, v245
	s_nop 1
	v_permlane32_swap_b32 v246, v245
	v_add_f32_e32 v245, v246, v245
	v_mov_b32_e32 v246, 0x3c000000
	v_fmaak_f32 v245, v245, v246, 0x358637bd
	v_rsq_f32_e32 v245, v245
	s_nop 0
	v_mul_f32_e32 v245, 0x3f4ccccd, v245
	s_lshl_b32 s6, s11, 11
	s_add_i32 s6, s6, s15
	s_lshl_b32 s6, s6, 11
	s_lshl_b32 s7, s81, 1
	s_add_i32 s6, s6, s7
	s_add_u32 s20, s70, s6
	s_addc_u32 s21, s71, 0
	v_and_b32_e32 v242, 31, v219
	v_lshlrev_b32_e32 v242, 11, v242
	v_lshrrev_b32_e32 v243, 5, v219
	v_lshl_add_u32 v242, v243, 4, v242
	s_waitcnt vmcnt(0)
; __device__ __forceinline__ unsigned pk_bf16(float lo, float hi) { f32x2 v = {lo, hi}; bf16x2_t b = __builtin_convertvector(v, bf16x2_t); return __builtin_bit_cast(unsigned, b); }
; __device__ __forceinline__ void subln_store(f32x16 (&o)[4], const float* subg, bf16_t* dst  , int lane) {
;     ...
; #pragma unroll
;     for (int cb = 0; cb < 4; ++cb)
; #pragma unroll
;         for (int g = 0; g < 4; ++g) { const int dv0 = 32 * cb + 8 * g + 4 * hi; const f32x4 s4 = sg[cb][g];
;             u32x2 w; w.x = pk_bf16(o[cb][4 * g + 0] * rstd * s4[0], o[cb][4 * g + 1] * rstd * s4[1]); w.y = pk_bf16(o[cb][4 * g + 2] * rstd * s4[2], o[cb][4 * g + 3] * rstd * s4[3]);
;             *(u32x2*)(dst + dv0) = w; }
	v_mul_f32_e32 v4, v4, v245
	v_mul_f32_e32 v5, v5, v245
	v_mul_f32_e32 v6, v6, v245
	v_mul_f32_e32 v7, v7, v245
	v_mul_f32_e32 v4, v4, v100
	v_mul_f32_e32 v5, v5, v101
	v_mul_f32_e32 v6, v6, v102
	v_mul_f32_e32 v7, v7, v103
	v_mul_f32_e32 v8, v8, v245
	v_mul_f32_e32 v9, v9, v245
	v_mul_f32_e32 v10, v10, v245
	v_mul_f32_e32 v11, v11, v245
	v_mul_f32_e32 v8, v8, v104
	v_mul_f32_e32 v9, v9, v105
	v_mul_f32_e32 v10, v10, v106
	v_mul_f32_e32 v11, v11, v107
	v_cvt_pk_bf16_f32 v68, v4, v5
	v_cvt_pk_bf16_f32 v69, v6, v7
	v_cvt_pk_bf16_f32 v70, v8, v9
	v_cvt_pk_bf16_f32 v71, v10, v11
	s_nop 1
	v_permlane32_swap_b32 v68, v70
	v_permlane32_swap_b32 v69, v71
	global_store_dwordx4 v242, v[68:71], s[20:21] offset:0
	v_mul_f32_e32 v12, v12, v245
	v_mul_f32_e32 v13, v13, v245
	v_mul_f32_e32 v14, v14, v245
	v_mul_f32_e32 v15, v15, v245
	v_mul_f32_e32 v12, v12, v108
	v_mul_f32_e32 v13, v13, v109
	v_mul_f32_e32 v14, v14, v110
	v_mul_f32_e32 v15, v15, v111
	v_mul_f32_e32 v16, v16, v245
	v_mul_f32_e32 v17, v17, v245
	v_mul_f32_e32 v18, v18, v245
	v_mul_f32_e32 v19, v19, v245
	v_mul_f32_e32 v16, v16, v112
	v_mul_f32_e32 v17, v17, v113
	v_mul_f32_e32 v18, v18, v114
	v_mul_f32_e32 v19, v19, v115
	v_cvt_pk_bf16_f32 v72, v12, v13
	v_cvt_pk_bf16_f32 v73, v14, v15
	v_cvt_pk_bf16_f32 v74, v16, v17
	v_cvt_pk_bf16_f32 v75, v18, v19
	s_nop 1
	v_permlane32_swap_b32 v72, v74
	v_permlane32_swap_b32 v73, v75
	global_store_dwordx4 v242, v[72:75], s[20:21] offset:32
	v_mul_f32_e32 v20, v20, v245
	v_mul_f32_e32 v21, v21, v245
	v_mul_f32_e32 v22, v22, v245
	v_mul_f32_e32 v23, v23, v245
	v_mul_f32_e32 v20, v20, v116
	v_mul_f32_e32 v21, v21, v117
	v_mul_f32_e32 v22, v22, v118
	v_mul_f32_e32 v23, v23, v119
	v_mul_f32_e32 v24, v24, v245
	v_mul_f32_e32 v25, v25, v245
	v_mul_f32_e32 v26, v26, v245
	v_mul_f32_e32 v27, v27, v245
	v_mul_f32_e32 v24, v24, v120
	v_mul_f32_e32 v25, v25, v121
	v_mul_f32_e32 v26, v26, v122
	v_mul_f32_e32 v27, v27, v123
	v_cvt_pk_bf16_f32 v68, v20, v21
	v_cvt_pk_bf16_f32 v69, v22, v23
	v_cvt_pk_bf16_f32 v70, v24, v25
	v_cvt_pk_bf16_f32 v71, v26, v27
	s_nop 1
	v_permlane32_swap_b32 v68, v70
	v_permlane32_swap_b32 v69, v71
	global_store_dwordx4 v242, v[68:71], s[20:21] offset:64
	v_mul_f32_e32 v28, v28, v245
	v_mul_f32_e32 v29, v29, v245
	v_mul_f32_e32 v30, v30, v245
	v_mul_f32_e32 v31, v31, v245
	v_mul_f32_e32 v28, v28, v124
	v_mul_f32_e32 v29, v29, v125
	v_mul_f32_e32 v30, v30, v126
	v_mul_f32_e32 v31, v31, v127
	v_mul_f32_e32 v32, v32, v245
	v_mul_f32_e32 v33, v33, v245
	v_mul_f32_e32 v34, v34, v245
	v_mul_f32_e32 v35, v35, v245
	v_mul_f32_e32 v32, v32, v128
	v_mul_f32_e32 v33, v33, v129
	v_mul_f32_e32 v34, v34, v130
	v_mul_f32_e32 v35, v35, v131
	v_cvt_pk_bf16_f32 v72, v28, v29
	v_cvt_pk_bf16_f32 v73, v30, v31
	v_cvt_pk_bf16_f32 v74, v32, v33
	v_cvt_pk_bf16_f32 v75, v34, v35
	s_nop 1
	v_permlane32_swap_b32 v72, v74
	v_permlane32_swap_b32 v73, v75
	global_store_dwordx4 v242, v[72:75], s[20:21] offset:96
	v_mul_f32_e32 v36, v36, v245
	v_mul_f32_e32 v37, v37, v245
	v_mul_f32_e32 v38, v38, v245
	v_mul_f32_e32 v39, v39, v245
	v_mul_f32_e32 v36, v36, v132
	v_mul_f32_e32 v37, v37, v133
	v_mul_f32_e32 v38, v38, v134
	v_mul_f32_e32 v39, v39, v135
	v_mul_f32_e32 v40, v40, v245
	v_mul_f32_e32 v41, v41, v245
	v_mul_f32_e32 v42, v42, v245
	v_mul_f32_e32 v43, v43, v245
	v_mul_f32_e32 v40, v40, v136
	v_mul_f32_e32 v41, v41, v137
	v_mul_f32_e32 v42, v42, v138
	v_mul_f32_e32 v43, v43, v139
	v_cvt_pk_bf16_f32 v68, v36, v37
	v_cvt_pk_bf16_f32 v69, v38, v39
	v_cvt_pk_bf16_f32 v70, v40, v41
	v_cvt_pk_bf16_f32 v71, v42, v43
	s_nop 1
	v_permlane32_swap_b32 v68, v70
	v_permlane32_swap_b32 v69, v71
	global_store_dwordx4 v242, v[68:71], s[20:21] offset:128
	v_mul_f32_e32 v44, v44, v245
	v_mul_f32_e32 v45, v45, v245
	v_mul_f32_e32 v46, v46, v245
	v_mul_f32_e32 v47, v47, v245
	v_mul_f32_e32 v44, v44, v140
	v_mul_f32_e32 v45, v45, v141
	v_mul_f32_e32 v46, v46, v142
	v_mul_f32_e32 v47, v47, v143
	v_mul_f32_e32 v48, v48, v245
	v_mul_f32_e32 v49, v49, v245
	v_mul_f32_e32 v50, v50, v245
	v_mul_f32_e32 v51, v51, v245
	v_mul_f32_e32 v48, v48, v144
	v_mul_f32_e32 v49, v49, v145
	v_mul_f32_e32 v50, v50, v146
	v_mul_f32_e32 v51, v51, v147
	v_cvt_pk_bf16_f32 v72, v44, v45
	v_cvt_pk_bf16_f32 v73, v46, v47
	v_cvt_pk_bf16_f32 v74, v48, v49
	v_cvt_pk_bf16_f32 v75, v50, v51
	s_nop 1
	v_permlane32_swap_b32 v72, v74
	v_permlane32_swap_b32 v73, v75
	global_store_dwordx4 v242, v[72:75], s[20:21] offset:160
	v_mul_f32_e32 v52, v52, v245
	v_mul_f32_e32 v53, v53, v245
	v_mul_f32_e32 v54, v54, v245
	v_mul_f32_e32 v55, v55, v245
	v_mul_f32_e32 v52, v52, v148
	v_mul_f32_e32 v53, v53, v149
	v_mul_f32_e32 v54, v54, v150
	v_mul_f32_e32 v55, v55, v151
	v_mul_f32_e32 v56, v56, v245
	v_mul_f32_e32 v57, v57, v245
	v_mul_f32_e32 v58, v58, v245
	v_mul_f32_e32 v59, v59, v245
	v_mul_f32_e32 v56, v56, v152
	v_mul_f32_e32 v57, v57, v153
	v_mul_f32_e32 v58, v58, v154
	v_mul_f32_e32 v59, v59, v155
	v_cvt_pk_bf16_f32 v68, v52, v53
	v_cvt_pk_bf16_f32 v69, v54, v55
	v_cvt_pk_bf16_f32 v70, v56, v57
	v_cvt_pk_bf16_f32 v71, v58, v59
	s_nop 1
	v_permlane32_swap_b32 v68, v70
	v_permlane32_swap_b32 v69, v71
	global_store_dwordx4 v242, v[68:71], s[20:21] offset:192
	v_mul_f32_e32 v60, v60, v245
	v_mul_f32_e32 v61, v61, v245
	v_mul_f32_e32 v62, v62, v245
	v_mul_f32_e32 v63, v63, v245
	v_mul_f32_e32 v60, v60, v156
	v_mul_f32_e32 v61, v61, v157
	v_mul_f32_e32 v62, v62, v158
	v_mul_f32_e32 v63, v63, v159
	v_mul_f32_e32 v64, v64, v245
	v_mul_f32_e32 v65, v65, v245
	v_mul_f32_e32 v66, v66, v245
	v_mul_f32_e32 v67, v67, v245
	v_mul_f32_e32 v64, v64, v160
	v_mul_f32_e32 v65, v65, v161
	v_mul_f32_e32 v66, v66, v162
	v_mul_f32_e32 v67, v67, v163
	v_cvt_pk_bf16_f32 v72, v60, v61
	v_cvt_pk_bf16_f32 v73, v62, v63
	v_cvt_pk_bf16_f32 v74, v64, v65
	v_cvt_pk_bf16_f32 v75, v66, v67
	s_nop 1
	v_permlane32_swap_b32 v72, v74
	v_permlane32_swap_b32 v73, v75
	global_store_dwordx4 v242, v[72:75], s[20:21] offset:224
